# cmp/window attention passes: half-workgroup stagger and mid-tile barrier removed (one workgroup barrier per tile, lockstep halves)
# speedup vs baseline: 1.0026x; 1.0026x over previous
; #define ATT_BAR() asm volatile("s_waitcnt lgkmcnt(0)\n\ts_barrier" ::: "memory")
; template <int DQK, int MODE> __device__ __forceinline__ void attn_pass(LAS unsigned char* lds, const bf16* K0, int p0, const bf16* K1, int p1, const bf16* V, int pv, int tlo, int thi, ...
;     asm volatile("" : "+v"(tid)); asm volatile("" : "+s"(K0), "+s"(V)); if (DQK == 96) asm volatile("" : "+s"(K1));
;     fr = tid & 15; fq = (tid & 63) >> 4;
;     const int grp = __builtin_amdgcn_readfirstlane(tid >> 8);
;     float m[2] = {NEG, NEG}, l[2] = {0.f, 0.f};
; #pragma unroll
;     for (int i = 0; i < 2; ++i)
; #pragma unroll
;         for (int dt = 0; dt < 4; ++dt) o[i][dt] = (f32x4){0.f, 0.f, 0.f, 0.f};
;     Stage<DQK> st;
;     {
;         Stage<DQK> st1;
;         stage_load<DQK>(st, K0, p0, K1, p1, V, pv, tlo, true, tid);
;         if (tlo < thi) stage_load<DQK>(st1, K0, p0, K1, p1, V, pv, tlo + 1, true, tid);
;         stage_store<DQK>(st, lds, true, tid);
;         if (tlo < thi) stage_store<DQK>(st1, lds + KL<DQK>::SLOT, true, tid);
;     }
;     ATT_BAR();
;     if (grp == 1) { ATT_BAR(); __builtin_amdgcn_s_setprio(1); }
;     int slot = 0;
;     f32x4 s[2][4];
;     for (int t = tlo; t <= thi; ++t) {
.LBB0_989:
	s_waitcnt lgkmcnt(0)
	s_barrier
	s_and_b32 s10, s18, 0xffffff00
	s_cmpk_lg_i32 s10, 0x100
	s_cbranch_scc1 .LBB0_991
	s_waitcnt lgkmcnt(0)
.LBB0_991:
	v_lshrrev_b32_e32 v16, 4, v28
	v_bfe_u32 v19, v28, 1, 3
	v_bfe_u32 v17, v28, 4, 2
	v_bitop3_b32 v16, v16, v19, 3 bitop3:0x6c
	v_lshlrev_b32_e32 v121, 4, v16
	v_bitop3_b32 v16, v17, v19, 4 bitop3:0x36
	v_and_b32_e32 v18, 15, v28
	v_lshlrev_b32_e32 v122, 4, v16
	v_bfe_u32 v16, v28, 2, 2
	v_lshlrev_b32_e32 v123, 6, v17
	v_lshl_or_b32 v16, v17, 2, v16
	v_lshlrev_b32_e32 v17, 2, v18
	v_lshlrev_b32_e32 v120, 7, v18
	v_and_b32_e32 v18, 12, v17
	v_mul_u32_u24_e32 v19, 0x50, v16
	v_or_b32_e32 v20, v19, v18
	v_mad_u32_u24 v16, v16, s79, v184
	v_lshlrev_b32_e32 v124, 1, v20
	v_or_b32_e32 v20, v16, v18
	v_lshlrev_b32_e32 v125, 1, v20
	v_or_b32_e32 v20, 16, v18
	v_or_b32_e32 v18, 32, v18
	v_or_b32_e32 v17, 48, v17
	v_add_lshl_u32 v127, v16, v20, 1
	v_add_lshl_u32 v129, v16, v18, 1
	v_add_lshl_u32 v131, v16, v17, 1
	v_and_b32_e32 v16, 7, v28
	v_lshlrev_b32_e32 v146, 4, v16
	v_add_lshl_u32 v130, v19, v17, 1
	v_lshl_add_u64 v[16:17], v[24:25], 0, v[146:147]
	v_add_lshl_u32 v126, v19, v20, 1
	v_add_lshl_u32 v128, v19, v18, 1
	v_lshl_add_u64 v[18:19], s[8:9], 0, v[16:17]
	s_lshr_b32 s64, s72, 4
	v_lshl_add_u64 v[106:107], v[18:19], 0, s[44:45]
	v_lshl_add_u64 v[16:17], s[6:7], 0, v[16:17]
	v_mov_b32_e32 v18, v147
	v_mov_b32_e32 v19, v147
	v_add_u32_e32 v113, s73, v170
	s_lshl_b32 s65, s64, 10
	v_lshl_add_u64 v[108:109], v[16:17], 0, s[44:45]
	v_mov_b32_e32 v146, v147
	v_mov_b32_e32 v16, v147
	v_mov_b32_e32 v17, v147
	v_mov_b32_e32 v56, 0
	v_mov_b64_e32 v[22:23], v[18:19]
	v_mov_b64_e32 v[26:27], v[18:19]
	v_mov_b64_e32 v[30:31], v[18:19]
	v_mov_b64_e32 v[34:35], v[18:19]
	v_mov_b64_e32 v[38:39], v[18:19]
	v_mov_b64_e32 v[42:43], v[18:19]
	v_mov_b64_e32 v[46:47], v[18:19]
	v_add_u32_e32 v114, s73, v171
	v_or_b32_e32 v136, 7, v113
	v_add_u32_e32 v116, s73, v172
	s_mov_b32 s20, 2
	s_addk_i32 s65, 0x400
	s_mov_b32 s21, 0
	v_mov_b32_e32 v110, 0xf149f2ca
	v_mov_b64_e32 v[20:21], v[16:17]
	v_mov_b64_e32 v[24:25], v[16:17]
	v_mov_b64_e32 v[28:29], v[16:17]
	v_mov_b64_e32 v[32:33], v[16:17]
	v_mov_b64_e32 v[36:37], v[16:17]
	v_mov_b64_e32 v[40:41], v[16:17]
	v_mov_b64_e32 v[44:45], v[16:17]
	s_mov_b32 s66, 0
	v_mov_b32_e32 v111, 0xf149f2ca
	v_mov_b64_e32 v[104:105], v[146:147]
	v_mov_b32_e32 v57, v56
	v_mov_b32_e32 v58, v56
	v_mov_b32_e32 v59, v56
	v_mov_b32_e32 v60, v56
	v_mov_b32_e32 v61, v56
	v_mov_b32_e32 v62, v56
	v_mov_b32_e32 v63, v56
	v_mov_b32_e32 v64, v56
	v_mov_b32_e32 v65, v56
	v_mov_b32_e32 v66, v56
	v_mov_b32_e32 v67, v56
	v_mov_b32_e32 v68, v56
	v_mov_b32_e32 v69, v56
	v_mov_b32_e32 v70, v56
	v_mov_b32_e32 v71, v56
	v_mov_b32_e32 v72, v56
	v_mov_b32_e32 v73, v56
	v_mov_b32_e32 v74, v56
	v_mov_b32_e32 v75, v56
	v_mov_b32_e32 v76, v56
	v_mov_b32_e32 v77, v56
	v_mov_b32_e32 v78, v56
	v_mov_b32_e32 v79, v56
	v_mov_b32_e32 v80, v56
	v_mov_b32_e32 v81, v56
	v_mov_b32_e32 v82, v56
	v_mov_b32_e32 v83, v56
	v_mov_b32_e32 v84, v56
	v_mov_b32_e32 v85, v56
	v_mov_b32_e32 v86, v56
	v_mov_b32_e32 v87, v56
	s_branch .LBB0_993

; #define LAS __attribute__((address_space(3)))
; __device__ __forceinline__ unsigned cvtpk(float lo, float hi) { f32x2_t v = {lo, hi}; bf16x2_t b = __builtin_convertvector(v, bf16x2_t); return __builtin_bit_cast(unsigned, b); }
; #define ATT_BAR() asm volatile("s_waitcnt lgkmcnt(0)\n\ts_barrier" ::: "memory")
; template <int I0, int NQ, int VO> __device__ __forceinline__ void tile_y(LAS unsigned char* lds, float (&l)[2], f32x4 (&o)[2][4], f32x4 (&s)[2][4], int fr, int fq) {
;     bf16x8 pb[NQ][2];
; #pragma unroll
;     for (int q = 0; q < NQ; ++q) {
;         f32x4 (&sq)[4] = s[I0 + q];
;         f32x2_t rs2 = {0.f, 0.f};
; #pragma unroll
;         for (int ss = 0; ss < 4; ++ss) {
; #pragma unroll
;             for (int i = 0; i < 4; ++i) sq[ss][i] = __builtin_amdgcn_exp2f(sq[ss][i]);
;             rs2 += (f32x2_t){sq[ss][0], sq[ss][1]}; rs2 += (f32x2_t){sq[ss][2], sq[ss][3]};
;         }
;         l[I0 + q] += rs2.x + rs2.y;
; #pragma unroll
;         for (int j = 0; j < 2; ++j) {
;             const v4u w = (v4u){cvtpk(sq[2 * j][0], sq[2 * j][1]), cvtpk(sq[2 * j][2], sq[2 * j][3]), cvtpk(sq[2 * j + 1][0], sq[2 * j + 1][1]), cvtpk(sq[2 * j + 1][2], sq[2 * j + 1][3])};
;             pb[q][j] = __builtin_bit_cast(bf16x8, w);
;         }
;     }
; #pragma unroll
;     for (int dt = 0; dt < 4; ++dt)
; #pragma unroll
;         for (int j = 0; j < 2; ++j) {
;             LAS unsigned char* vp = lds + VO + ((32 * j + 4 * fq + (fr >> 2)) * VSTR + 16 * dt + 4 * (fr & 3)) * 2;
;             const s16x4 lo = __builtin_bit_cast(s16x4, __builtin_amdgcn_ds_read_tr16_b64_v4i16((LAS v4i16_t*)vp));
;             const s16x4 hi = __builtin_bit_cast(s16x4, __builtin_amdgcn_ds_read_tr16_b64_v4i16((LAS v4i16_t*)(vp + 16 * VSTR * 2)));
;             const bf16x8 vf = (bf16x8){lo[0], lo[1], lo[2], lo[3], hi[0], hi[1], hi[2], hi[3]};
; #pragma unroll
;             for (int q = 0; q < NQ; ++q) o[I0 + q][dt] = __builtin_amdgcn_mfma_f32_16x16x32_bf16(vf, pb[q][j], o[I0 + q][dt], 0, 0, 0);
;         }
; }
; template <int DQK, int MODE> __device__ __forceinline__ void attn_pass(LAS unsigned char* lds, const bf16* K0, int p0, const bf16* K1, int p1, const bf16* V, int pv, int tlo, int thi, ...
;     ...
;         ATT_BAR();
;         if (code == 1) { __builtin_amdgcn_iglp_opt(1); tile_y<0, 2, KL<DQK>::VOFF>(buf, l, o, s, fr, fq); }
.LBB0_1010:
	s_or_b64 exec, exec, s[60:61]
	s_waitcnt lgkmcnt(0)
	s_and_saveexec_b64 s[8:9], s[6:7]
	s_cbranch_execz .LBB0_1012
	s_waitcnt lgkmcnt(0)
	v_add_u32_e32 v98, s87, v124
	ds_read_b64_tr_b16 v[96:97], v98 offset:8192
	ds_read_b64_tr_b16 v[98:99], v98 offset:10752
	v_add_u32_e32 v134, s87, v125
	v_exp_f32_e32 v56, v56
	v_exp_f32_e32 v57, v57
	v_exp_f32_e32 v58, v58
	v_exp_f32_e32 v59, v59
	v_exp_f32_e32 v60, v60
	v_exp_f32_e32 v61, v61
	v_exp_f32_e32 v62, v62
	v_exp_f32_e32 v63, v63
	v_exp_f32_e32 v72, v72
	v_exp_f32_e32 v73, v73
	v_exp_f32_e32 v74, v74
	v_exp_f32_e32 v75, v75
	v_exp_f32_e32 v76, v76
	v_exp_f32_e32 v77, v77
	v_exp_f32_e32 v78, v78
	v_exp_f32_e32 v79, v79
	ds_read_b64_tr_b16 v[132:133], v134 offset:8192
	ds_read_b64_tr_b16 v[134:135], v134 offset:10752
	v_exp_f32_e32 v64, v64
	v_exp_f32_e32 v65, v65
	v_exp_f32_e32 v66, v66
	v_exp_f32_e32 v67, v67
	v_exp_f32_e32 v68, v68
	v_exp_f32_e32 v69, v69
	v_exp_f32_e32 v70, v70
	v_exp_f32_e32 v71, v71
	v_cvt_pk_bf16_f32 v88, v56, v57
	v_cvt_pk_bf16_f32 v89, v58, v59
	v_cvt_pk_bf16_f32 v90, v60, v61
	v_cvt_pk_bf16_f32 v91, v62, v63
	v_exp_f32_e32 v80, v80
	v_exp_f32_e32 v81, v81
	v_exp_f32_e32 v82, v82
	v_exp_f32_e32 v83, v83
	v_exp_f32_e32 v84, v84
	v_exp_f32_e32 v85, v85
	v_exp_f32_e32 v86, v86
	v_exp_f32_e32 v87, v87
	v_cvt_pk_bf16_f32 v100, v72, v73
	v_cvt_pk_bf16_f32 v101, v74, v75
	v_cvt_pk_bf16_f32 v102, v76, v77
	v_cvt_pk_bf16_f32 v103, v78, v79
	v_add_u32_e32 v137, s87, v126
	s_waitcnt lgkmcnt(0)
	v_mfma_f32_16x16x32_bf16 v[44:47], v[96:99], v[88:91], v[44:47]
	ds_read_b64_tr_b16 v[156:157], v137 offset:8192
	v_cvt_pk_bf16_f32 v92, v64, v65
	v_cvt_pk_bf16_f32 v93, v66, v67
	v_mfma_f32_16x16x32_bf16 v[28:31], v[96:99], v[100:103], v[28:31]
	ds_read_b64_tr_b16 v[158:159], v137 offset:10752
	v_cvt_pk_bf16_f32 v94, v68, v69
	v_cvt_pk_bf16_f32 v95, v70, v71
	v_cvt_pk_bf16_f32 v138, v80, v81
	v_cvt_pk_bf16_f32 v139, v82, v83
	v_cvt_pk_bf16_f32 v140, v84, v85
	v_cvt_pk_bf16_f32 v141, v86, v87
	v_add_u32_e32 v98, s87, v127
	v_mfma_f32_16x16x32_bf16 v[44:47], v[132:135], v[92:95], v[44:47]
	ds_read_b64_tr_b16 v[96:97], v98 offset:8192
	v_add_u32_e32 v137, s87, v128
	v_mfma_f32_16x16x32_bf16 v[28:31], v[132:135], v[138:141], v[28:31]
	ds_read_b64_tr_b16 v[98:99], v98 offset:10752
	v_add_f32_e64 v134, v56, 0
	v_add_f32_e64 v135, v57, 0
	s_nop 0
	v_add_f32_e32 v134, v58, v134
	v_add_f32_e32 v135, v59, v135
	s_waitcnt lgkmcnt(0)
	v_mfma_f32_16x16x32_bf16 v[40:43], v[156:159], v[88:91], v[40:43]
	ds_read_b64_tr_b16 v[132:133], v137 offset:8192
	v_add_f32_e32 v142, v60, v134
	v_add_f32_e32 v143, v61, v135
	v_mfma_f32_16x16x32_bf16 v[24:27], v[156:159], v[100:103], v[24:27]
	ds_read_b64_tr_b16 v[134:135], v137 offset:10752
	v_add_u32_e32 v137, s87, v129
	v_add_f32_e32 v142, v62, v142
	v_add_f32_e32 v143, v63, v143
	v_mfma_f32_16x16x32_bf16 v[40:43], v[96:99], v[92:95], v[40:43]
	ds_read_b64_tr_b16 v[156:157], v137 offset:8192
	v_mfma_f32_16x16x32_bf16 v[24:27], v[96:99], v[138:141], v[24:27]
	ds_read_b64_tr_b16 v[158:159], v137 offset:10752
	v_add_f32_e32 v96, v64, v142
	v_add_f32_e32 v97, v65, v143
	v_add_u32_e32 v137, s87, v130
	v_add_f32_e32 v96, v66, v96
	v_add_f32_e32 v97, v67, v97
	s_waitcnt lgkmcnt(0)
	v_mfma_f32_16x16x32_bf16 v[36:39], v[132:135], v[88:91], v[36:39]
	v_add_f32_e64 v98, v68, v96
	v_add_f32_e64 v99, v69, v97
	ds_read_b64_tr_b16 v[96:97], v137 offset:8192
	v_add_f32_e32 v142, v70, v98
	v_add_f32_e32 v143, v71, v99
	v_mfma_f32_16x16x32_bf16 v[20:23], v[132:135], v[100:103], v[20:23]
	ds_read_b64_tr_b16 v[98:99], v137 offset:10752
	v_add_f32_e64 v132, v72, 0
	v_add_f32_e64 v133, v73, 0
	v_add_u32_e32 v137, s87, v131
	v_add_f32_e32 v134, v74, v132
	v_add_f32_e32 v135, v75, v133
	v_mfma_f32_16x16x32_bf16 v[36:39], v[156:159], v[92:95], v[36:39]
	v_add_f32_e64 v134, v76, v134
	v_add_f32_e64 v135, v77, v135
	ds_read_b64_tr_b16 v[132:133], v137 offset:8192
	v_mfma_f32_16x16x32_bf16 v[20:23], v[156:159], v[138:141], v[20:23]
	v_add_f32_e64 v156, v78, v134
	v_add_f32_e64 v157, v79, v135
	ds_read_b64_tr_b16 v[134:135], v137 offset:10752
	s_waitcnt lgkmcnt(0)
	v_mfma_f32_16x16x32_bf16 v[32:35], v[96:99], v[88:91], v[32:35]
	v_add_f32_e64 v88, v80, v156
	v_add_f32_e64 v89, v81, v157
	v_mov_b32_e32 v90, v142
	v_add_f32_e32 v88, v82, v88
	v_add_f32_e32 v89, v83, v89
	v_mfma_f32_16x16x32_bf16 v[16:19], v[96:99], v[100:103], v[16:19]
	v_add_f32_e64 v88, v84, v88
	v_add_f32_e64 v89, v85, v89
	v_add_f32_e32 v88, v86, v88
	v_add_f32_e32 v89, v87, v89
	v_mfma_f32_16x16x32_bf16 v[32:35], v[132:135], v[92:95], v[32:35]
	v_mov_b32_e32 v91, v88
	v_mov_b32_e32 v88, v143
	v_add_f32_e32 v88, v90, v88
	v_add_f32_e32 v89, v91, v89
	v_mfma_f32_16x16x32_bf16 v[16:19], v[132:135], v[138:141], v[16:19]
	v_add_f32_e64 v104, v104, v88
	v_add_f32_e64 v105, v105, v89

; #define ATT_BAR() asm volatile("s_waitcnt lgkmcnt(0)\n\ts_barrier" ::: "memory")
; __device__ __forceinline__ v4u pack8(const f32x4& a, const f32x4& b) { return (v4u){cvtpk(a[0], a[1]), cvtpk(a[2], a[3]), cvtpk(b[0], b[1]), cvtpk(b[2], b[3])}; }
; template <int DQK, int MODE> __device__ __forceinline__ void attn_pass(LAS unsigned char* lds, const bf16* K0, int p0, const bf16* K1, int p1, const bf16* V, int pv, int tlo, int thi, ...
;     ...
;     if (grp == 0) ATT_BAR(); else __builtin_amdgcn_s_setprio(0);
; #pragma unroll
;     for (int i = 0; i < 2; ++i) {
;         const float lt = rows_sum(l[i]);
;         const float iv = lt > 0.f ? 1.0f / lt : 0.f;
;         mfin[i] = m[i]; linv[i] = iv;
; #pragma unroll
;         for (int dt = 0; dt < 4; ++dt) o[i][dt] = o[i][dt] * iv;
;     }
; __device__ __forceinline__ void nsa_item(LAS unsigned char* lds, const NsaPtrs& P, int b, int g, int qb, int tid) {
;     ...
;     for (int i = 0; i < 2; ++i) { const float gc = P.GATES[((size_t)b * T + tpos[i]) * 24 + g * 12 + hh * 3 + 0];
;         ocl[(i * 2 + 0) * NTHREADS + tid] = pack8(o[i][0] * gc, o[i][1] * gc); ocl[(i * 2 + 1) * NTHREADS + tid] = pack8(o[i][2] * gc, o[i][3] * gc); }
;     ...
;     int tid_i = tid; asm volatile("" : "+v"(tid_i)); const int fr_i = tid_i & 15, fq_i = (tid_i & 63) >> 4; asm volatile("" : "+s"(Kc));
;     v4u kpre = *(const v4u*)(Kc + (size_t)(tid_i >> 3) * 64 + 8 * (tid_i & 7));
.LBB0_1016:
	s_andn2_b64 vcc, exec, s[6:7]
	s_cbranch_vccnz .LBB0_1018
	s_waitcnt lgkmcnt(0)
.LBB0_1018:
	s_add_u32 s56, s54, 0x3600000
	s_addc_u32 s57, s55, 0
	v_mov_b32_e32 v115, v147
	v_lshl_add_u64 v[120:121], s[46:47], 0, v[114:115]
	s_waitcnt vmcnt(0) lgkmcnt(0)
	v_mov_b64_e32 v[48:49], s[56:57]
	v_mad_u64_u32 v[50:51], s[6:7], v120, s84, v[48:49]
	v_mad_i32_i24 v51, v121, s84, v51
	s_lshl_b32 s18, s71, 2
	v_lshl_add_u64 v[50:51], v[50:51], 0, s[18:19]
	v_mov_b32_e32 v153, v147
	v_lshl_add_u64 v[128:129], v[50:51], 0, v[152:153]
	global_load_dword v50, v[128:129], off
	v_mov_b32_e32 v51, v104
	v_mov_b32_e32 v52, v105
	s_nop 0
	v_permlane16_swap_b32_e32 v104, v51
	v_permlane16_swap_b32_e32 v105, v52
	v_add_f32_e32 v53, v104, v51
	v_add_f32_e32 v52, v105, v52
	v_mov_b32_e32 v55, v53
	v_mov_b32_e32 v54, v52
	s_nop 0
	v_permlane32_swap_b32_e32 v53, v55
	v_permlane32_swap_b32_e32 v52, v54
	v_pk_add_f32 v[52:53], v[52:53], v[54:55]
	v_mov_b32_e32 v117, v147
	v_div_scale_f32 v51, s[6:7], v53, v53, 1.0
	v_lshl_add_u64 v[118:119], s[46:47], 0, v[116:117]
	v_rcp_f32_e32 v54, v51
	v_mad_u64_u32 v[48:49], s[6:7], v118, s84, v[48:49]
	v_mad_i32_i24 v49, v119, s84, v49
	v_lshl_add_u64 v[48:49], v[48:49], 0, s[18:19]
	v_lshl_add_u64 v[126:127], v[48:49], 0, v[152:153]
	v_fma_f32 v48, -v51, v54, 1.0
	v_div_scale_f32 v55, vcc, 1.0, v53, 1.0
	v_fmac_f32_e32 v54, v48, v54
	v_mul_f32_e32 v48, v55, v54
	v_fma_f32 v49, -v51, v48, v55
	v_fmac_f32_e32 v48, v49, v54
	v_fma_f32 v49, -v51, v48, v55
	v_div_fmas_f32 v48, v49, v54, v48
	v_div_fixup_f32 v48, v48, v53, 1.0
	v_cmp_lt_f32_e32 vcc, 0, v53
	v_mad_u64_u32 v[124:125], s[6:7], v120, s84, 0
	s_nop 0
	v_cndmask_b32_e32 v64, 0, v48, vcc
	v_pk_mul_f32 v[44:45], v[44:45], v[64:65] op_sel_hi:[1,0]
	v_pk_mul_f32 v[46:47], v[46:47], v[64:65] op_sel_hi:[1,0]
	v_pk_mul_f32 v[40:41], v[40:41], v[64:65] op_sel_hi:[1,0]
	v_pk_mul_f32 v[42:43], v[42:43], v[64:65] op_sel_hi:[1,0]
	v_pk_mul_f32 v[36:37], v[36:37], v[64:65] op_sel_hi:[1,0]
	v_pk_mul_f32 v[38:39], v[38:39], v[64:65] op_sel_hi:[1,0]
	v_pk_mul_f32 v[32:33], v[32:33], v[64:65] op_sel_hi:[1,0]
	v_pk_mul_f32 v[34:35], v[34:35], v[64:65] op_sel_hi:[1,0]
	v_mad_u64_u32 v[122:123], s[6:7], v118, s84, 0
	v_mad_i32_i24 v125, v121, s84, v125
	v_mad_i32_i24 v123, v119, s84, v123
	s_mov_b32 s10, 0
	s_mov_b32 s11, 0
	s_waitcnt vmcnt(0) lgkmcnt(0)
	v_pk_mul_f32 v[46:47], v[50:51], v[46:47] op_sel_hi:[0,1]
	v_pk_mul_f32 v[44:45], v[50:51], v[44:45] op_sel_hi:[0,1]
	v_pk_mul_f32 v[42:43], v[50:51], v[42:43] op_sel_hi:[0,1]
	v_pk_mul_f32 v[40:41], v[50:51], v[40:41] op_sel_hi:[0,1]
	v_pk_mul_f32 v[38:39], v[50:51], v[38:39] op_sel_hi:[0,1]
	v_pk_mul_f32 v[36:37], v[50:51], v[36:37] op_sel_hi:[0,1]
	v_pk_mul_f32 v[48:49], v[50:51], v[34:35] op_sel_hi:[0,1]
	v_pk_mul_f32 v[50:51], v[50:51], v[32:33] op_sel_hi:[0,1]
	v_cvt_pk_bf16_f32 v32, v44, v45
	v_cvt_pk_bf16_f32 v33, v46, v47
	v_cvt_pk_bf16_f32 v34, v40, v41
	v_cvt_pk_bf16_f32 v35, v42, v43
	v_cvt_pk_bf16_f32 v36, v36, v37
	v_cvt_pk_bf16_f32 v37, v38, v39
	v_cvt_pk_bf16_f32 v38, v50, v51
	v_cvt_pk_bf16_f32 v39, v48, v49
	ds_write_b128 v173, v[32:35]
	ds_write_b128 v174, v[36:39]
	global_load_dword v32, v[126:127], off
	v_div_scale_f32 v33, s[6:7], v52, v52, 1.0
	v_rcp_f32_e32 v34, v33
	v_div_scale_f32 v35, vcc, 1.0, v52, 1.0
	v_mov_b32_e32 v36, v144
	v_fma_f32 v37, -v33, v34, 1.0
	v_fmac_f32_e32 v34, v37, v34
	v_mul_f32_e32 v37, v35, v34
	v_fma_f32 v38, -v33, v37, v35
	v_fmac_f32_e32 v37, v38, v34
	v_fma_f32 v33, -v33, v37, v35
	v_div_fmas_f32 v33, v33, v34, v37
	v_div_fixup_f32 v33, v33, v52, 1.0
	v_cmp_lt_f32_e32 vcc, 0, v52
	s_nop 1
	v_cndmask_b32_e32 v66, 0, v33, vcc
	v_pk_mul_f32 v[28:29], v[28:29], v[66:67] op_sel_hi:[1,0]
	v_pk_mul_f32 v[30:31], v[30:31], v[66:67] op_sel_hi:[1,0]
	v_pk_mul_f32 v[24:25], v[24:25], v[66:67] op_sel_hi:[1,0]
	v_pk_mul_f32 v[26:27], v[26:27], v[66:67] op_sel_hi:[1,0]
	v_pk_mul_f32 v[20:21], v[20:21], v[66:67] op_sel_hi:[1,0]
	v_pk_mul_f32 v[22:23], v[22:23], v[66:67] op_sel_hi:[1,0]
	v_pk_mul_f32 v[16:17], v[16:17], v[66:67] op_sel_hi:[1,0]
	v_pk_mul_f32 v[18:19], v[18:19], v[66:67] op_sel_hi:[1,0]
	s_waitcnt vmcnt(0) lgkmcnt(0)
	v_pk_mul_f32 v[30:31], v[32:33], v[30:31] op_sel_hi:[0,1]
	v_pk_mul_f32 v[28:29], v[32:33], v[28:29] op_sel_hi:[0,1]
	v_pk_mul_f32 v[26:27], v[32:33], v[26:27] op_sel_hi:[0,1]
	v_pk_mul_f32 v[24:25], v[32:33], v[24:25] op_sel_hi:[0,1]
	v_pk_mul_f32 v[20:21], v[32:33], v[20:21] op_sel_hi:[0,1]
	v_pk_mul_f32 v[22:23], v[32:33], v[22:23] op_sel_hi:[0,1]
	v_pk_mul_f32 v[34:35], v[32:33], v[18:19] op_sel_hi:[0,1]
	v_pk_mul_f32 v[32:33], v[32:33], v[16:17] op_sel_hi:[0,1]
	v_cvt_pk_bf16_f32 v16, v28, v29
	v_cvt_pk_bf16_f32 v17, v30, v31
	v_cvt_pk_bf16_f32 v18, v24, v25
	v_cvt_pk_bf16_f32 v19, v26, v27
	v_cvt_pk_bf16_f32 v20, v20, v21
	v_cvt_pk_bf16_f32 v21, v22, v23
	v_cvt_pk_bf16_f32 v22, v32, v33
	v_cvt_pk_bf16_f32 v23, v34, v35
	ds_write_b128 v175, v[16:19]
	ds_write_b128 v176, v[20:23]
	s_nop 0
	v_ashrrev_i32_e32 v20, 3, v36
	v_ashrrev_i32_e32 v21, 31, v20
	v_lshlrev_b32_e32 v18, 4, v36
	v_lshlrev_b64 v[22:23], 7, v[20:21]
	v_lshl_add_u64 v[16:17], s[14:15], 0, v[22:23]
	v_and_b32_e32 v146, 0x70, v18
	v_lshl_add_u64 v[16:17], v[16:17], 0, v[146:147]
	global_load_dwordx4 v[16:19], v[16:17], off
	v_lshlrev_b32_e32 v26, 7, v20
	v_lshrrev_b32_e32 v20, 1, v20
	v_xor_b32_e32 v20, v20, v36
	v_lshlrev_b32_e32 v20, 4, v20
	v_and_b32_e32 v20, 0x70, v20
	v_lshrrev_b32_e32 v24, 4, v36
	v_bfe_u32 v25, v36, 4, 2
	v_add_u32_e32 v27, 0, v20
	v_bfe_u32 v20, v36, 1, 3
	v_bitop3_b32 v24, v24, v20, 3 bitop3:0x6c
	v_bitop3_b32 v20, v25, v20, 4 bitop3:0x36
	v_lshlrev_b32_e32 v29, 4, v20
	v_and_b32_e32 v20, 7, v36
	v_and_b32_e32 v21, 15, v36
	v_lshl_or_b32 v22, v20, 4, v22
	v_lshl_add_u32 v28, v21, 7, 0
	v_lshlrev_b32_e32 v24, 4, v24
	v_cmp_gt_u32_e32 vcc, 4, v21
	v_lshl_add_u64 v[20:21], s[14:15], 0, v[22:23]
	v_lshlrev_b32_e32 v65, 6, v25
	v_lshl_add_u64 v[68:69], v[20:21], 0, s[38:39]
	v_lshl_add_u32 v67, v25, 2, v182
	v_add_u32_e32 v70, v27, v26
	v_add_u32_e32 v71, v28, v24
	v_add_u32_e32 v72, v28, v29
	v_lshlrev_b32_e32 v52, 4, v144
	v_add_u32_e32 v52, 0x2000, v52
	v_mov_b32_e32 v220, 0
	v_mov_b32_e32 v221, 0
	v_mov_b32_e32 v222, 0
	v_mov_b32_e32 v223, 0
	s_waitcnt lgkmcnt(0)
	s_barrier
	ds_write_b128 v52, v[220:223]
	ds_write_b128 v52, v[220:223] offset:8192
	ds_write_b128 v52, v[220:223] offset:16384
	ds_write_b128 v52, v[220:223] offset:24576
	v_cmp_gt_u32_e64 s[12:13], 64, v144
	s_nop 1
	s_and_saveexec_b64 s[14:15], s[12:13]
	ds_write_b128 v52, v[220:223] offset:32768
	s_or_b64 exec, exec, s[14:15]
	s_branch .LBB0_1020

; #define ATT_BAR() asm volatile("s_waitcnt lgkmcnt(0)\n\ts_barrier" ::: "memory")
; template <int DQK, int MODE> __device__ __forceinline__ void attn_pass(LAS unsigned char* lds, const bf16* K0, int p0, const bf16* K1, int p1, const bf16* V, int pv, int tlo, int thi, ...
;     asm volatile("" : "+v"(tid)); asm volatile("" : "+s"(K0), "+s"(V)); if (DQK == 96) asm volatile("" : "+s"(K1));
;     fr = tid & 15; fq = (tid & 63) >> 4;
;     const int grp = __builtin_amdgcn_readfirstlane(tid >> 8);
;     float m[2] = {NEG, NEG}, l[2] = {0.f, 0.f};
; #pragma unroll
;     for (int i = 0; i < 2; ++i)
; #pragma unroll
;         for (int dt = 0; dt < 4; ++dt) o[i][dt] = (f32x4){0.f, 0.f, 0.f, 0.f};
;     Stage<DQK> st;
;     {
;         Stage<DQK> st1;
;         stage_load<DQK>(st, K0, p0, K1, p1, V, pv, tlo, true, tid);
;         if (tlo < thi) stage_load<DQK>(st1, K0, p0, K1, p1, V, pv, tlo + 1, true, tid);
;         stage_store<DQK>(st, lds, true, tid);
;         if (tlo < thi) stage_store<DQK>(st1, lds + KL<DQK>::SLOT, true, tid);
;     }
;     ATT_BAR();
;     if (grp == 1) { ATT_BAR(); __builtin_amdgcn_s_setprio(1); }
;     int slot = 0;
;     f32x4 s[2][4];
;     for (int t = tlo; t <= thi; ++t) {
; __device__ __forceinline__ void nsa_item(LAS unsigned char* lds, const NsaPtrs& P, int b, int g, int qb, int tid) {
;     ...
;     attn_pass<64, WINDOW>(lds, P.KV6 + 4 * KV6_SEG + bg * T * 64, 64, nullptr, 0, P.KV6 + 5 * KV6_SEG + bg * T * 64, 64, (qb >= 8 ? qb - 8 : 0), qb, qf, tpos, tok, wave_tmin, wave_tmax, o, mf, li, tid, fr, fq);
.LBB0_1193:
	s_waitcnt lgkmcnt(0)
	s_barrier
	s_and_b32 s6, s20, 0xffffff00
	s_cmpk_lg_i32 s6, 0x100
	s_cbranch_scc1 .LBB0_1195
	s_waitcnt lgkmcnt(0)
.LBB0_1195:
	v_lshrrev_b32_e32 v0, 4, v12
	v_bfe_u32 v3, v12, 1, 3
	v_bfe_u32 v1, v12, 4, 2
	v_bitop3_b32 v0, v0, v3, 3 bitop3:0x6c
	v_lshlrev_b32_e32 v128, 4, v0
	v_bitop3_b32 v0, v1, v3, 4 bitop3:0x36
	v_and_b32_e32 v2, 15, v12
	v_lshlrev_b32_e32 v129, 4, v0
	v_lshlrev_b32_e32 v130, 2, v1
	v_bfe_u32 v0, v12, 2, 2
	v_or_b32_e32 v0, v130, v0
	v_lshlrev_b32_e32 v1, 2, v2
	v_lshlrev_b32_e32 v127, 7, v2
	v_and_b32_e32 v2, 12, v1
	v_mul_u32_u24_e32 v3, 0x50, v0
	v_or_b32_e32 v4, v3, v2
	v_mad_u32_u24 v0, v0, s79, v184
	v_lshlrev_b32_e32 v131, 1, v4
	v_or_b32_e32 v4, v0, v2
	v_lshlrev_b32_e32 v132, 1, v4
	v_or_b32_e32 v4, 16, v2
	v_or_b32_e32 v2, 32, v2
	v_or_b32_e32 v1, 48, v1
	s_min_u32 s6, s72, 8
	v_add_lshl_u32 v134, v0, v4, 1
	v_add_lshl_u32 v137, v0, v2, 1
	v_add_lshl_u32 v139, v0, v1, 1
	s_sub_i32 s21, s87, s6
	s_lshl_b32 s6, s6, 6
	v_add_u32_e32 v0, s73, v8
	v_subrev_u32_e32 v0, s6, v0
	v_add_u32_e32 v0, 0x80, v0
	v_add_lshl_u32 v138, v3, v1, 1
	v_ashrrev_i32_e32 v1, 31, v0
	v_add_lshl_u32 v135, v3, v2, 1
	v_lshlrev_b64 v[0:1], 7, v[0:1]
	v_and_b32_e32 v2, 7, v12
	v_add_lshl_u32 v133, v3, v4, 1
	v_lshl_or_b32 v0, v2, 4, v0
	v_mov_b32_e32 v2, v147
	v_mov_b32_e32 v3, v147
	v_lshl_add_u64 v[106:107], s[8:9], 0, v[0:1]
	v_lshl_add_u64 v[108:109], s[10:11], 0, v[0:1]
	v_mov_b32_e32 v146, v147
	v_mov_b32_e32 v0, v147
	v_mov_b32_e32 v1, v147
	v_mov_b32_e32 v56, 0
	v_mov_b64_e32 v[6:7], v[2:3]
	v_mov_b64_e32 v[10:11], v[2:3]
	v_mov_b64_e32 v[14:15], v[2:3]
	v_mov_b64_e32 v[18:19], v[2:3]
	v_mov_b64_e32 v[22:23], v[2:3]
	v_mov_b64_e32 v[26:27], v[2:3]
	v_mov_b64_e32 v[30:31], v[2:3]
	v_add_u32_e32 v126, 0xfffffe07, v113
	s_sub_i32 s62, s73, s6
	s_mov_b32 s63, 0
	v_mov_b32_e32 v140, 0xf149f2ca
	v_mov_b64_e32 v[4:5], v[0:1]
	v_mov_b64_e32 v[8:9], v[0:1]
	v_mov_b64_e32 v[12:13], v[0:1]
	v_mov_b64_e32 v[16:17], v[0:1]
	v_mov_b64_e32 v[20:21], v[0:1]
	v_mov_b64_e32 v[24:25], v[0:1]
	v_mov_b64_e32 v[28:29], v[0:1]
	v_mov_b32_e32 v141, 0xf149f2ca
	v_mov_b64_e32 v[104:105], v[146:147]
	v_mov_b32_e32 v57, v56
	v_mov_b32_e32 v58, v56
	v_mov_b32_e32 v59, v56
	v_mov_b32_e32 v60, v56
	v_mov_b32_e32 v61, v56
	v_mov_b32_e32 v62, v56
	v_mov_b32_e32 v63, v56
	v_mov_b32_e32 v64, v56
	v_mov_b32_e32 v65, v56
	v_mov_b32_e32 v66, v56
	v_mov_b32_e32 v67, v56
	v_mov_b32_e32 v68, v56
	v_mov_b32_e32 v69, v56
	v_mov_b32_e32 v70, v56
	v_mov_b32_e32 v71, v56
	v_mov_b32_e32 v72, v56
	v_mov_b32_e32 v73, v56
	v_mov_b32_e32 v74, v56
	v_mov_b32_e32 v75, v56
	v_mov_b32_e32 v76, v56
	v_mov_b32_e32 v77, v56
	v_mov_b32_e32 v78, v56
	v_mov_b32_e32 v79, v56
	v_mov_b32_e32 v80, v56
	v_mov_b32_e32 v81, v56
	v_mov_b32_e32 v82, v56
	v_mov_b32_e32 v83, v56
	v_mov_b32_e32 v84, v56
	v_mov_b32_e32 v85, v56
	v_mov_b32_e32 v86, v56
	v_mov_b32_e32 v87, v56
	s_branch .LBB0_1197

; #define LAS __attribute__((address_space(3)))
; __device__ __forceinline__ unsigned cvtpk(float lo, float hi) { f32x2_t v = {lo, hi}; bf16x2_t b = __builtin_convertvector(v, bf16x2_t); return __builtin_bit_cast(unsigned, b); }
; #define ATT_BAR() asm volatile("s_waitcnt lgkmcnt(0)\n\ts_barrier" ::: "memory")
; template <int I0, int NQ, int VO> __device__ __forceinline__ void tile_y(LAS unsigned char* lds, float (&l)[2], f32x4 (&o)[2][4], f32x4 (&s)[2][4], int fr, int fq) {
;     bf16x8 pb[NQ][2];
; #pragma unroll
;     for (int q = 0; q < NQ; ++q) {
;         f32x4 (&sq)[4] = s[I0 + q];
;         f32x2_t rs2 = {0.f, 0.f};
; #pragma unroll
;         for (int ss = 0; ss < 4; ++ss) {
; #pragma unroll
;             for (int i = 0; i < 4; ++i) sq[ss][i] = __builtin_amdgcn_exp2f(sq[ss][i]);
;             rs2 += (f32x2_t){sq[ss][0], sq[ss][1]}; rs2 += (f32x2_t){sq[ss][2], sq[ss][3]};
;         }
;         l[I0 + q] += rs2.x + rs2.y;
; #pragma unroll
;         for (int j = 0; j < 2; ++j) {
;             const v4u w = (v4u){cvtpk(sq[2 * j][0], sq[2 * j][1]), cvtpk(sq[2 * j][2], sq[2 * j][3]), cvtpk(sq[2 * j + 1][0], sq[2 * j + 1][1]), cvtpk(sq[2 * j + 1][2], sq[2 * j + 1][3])};
;             pb[q][j] = __builtin_bit_cast(bf16x8, w);
;         }
;     }
; #pragma unroll
;     for (int dt = 0; dt < 4; ++dt)
; #pragma unroll
;         for (int j = 0; j < 2; ++j) {
;             LAS unsigned char* vp = lds + VO + ((32 * j + 4 * fq + (fr >> 2)) * VSTR + 16 * dt + 4 * (fr & 3)) * 2;
;             const s16x4 lo = __builtin_bit_cast(s16x4, __builtin_amdgcn_ds_read_tr16_b64_v4i16((LAS v4i16_t*)vp));
;             const s16x4 hi = __builtin_bit_cast(s16x4, __builtin_amdgcn_ds_read_tr16_b64_v4i16((LAS v4i16_t*)(vp + 16 * VSTR * 2)));
;             const bf16x8 vf = (bf16x8){lo[0], lo[1], lo[2], lo[3], hi[0], hi[1], hi[2], hi[3]};
; #pragma unroll
;             for (int q = 0; q < NQ; ++q) o[I0 + q][dt] = __builtin_amdgcn_mfma_f32_16x16x32_bf16(vf, pb[q][j], o[I0 + q][dt], 0, 0, 0);
;         }
; }
; template <int DQK, int MODE> __device__ __forceinline__ void attn_pass(LAS unsigned char* lds, const bf16* K0, int p0, const bf16* K1, int p1, const bf16* V, int pv, int tlo, int thi, ...
;     ...
;         ATT_BAR();
;         if (code == 1) { __builtin_amdgcn_iglp_opt(1); tile_y<0, 2, KL<DQK>::VOFF>(buf, l, o, s, fr, fq); }
.LBB0_1214:
	s_or_b64 exec, exec, s[58:59]
	s_waitcnt lgkmcnt(0)
	s_and_saveexec_b64 s[8:9], s[6:7]
	s_cbranch_execz .LBB0_1216
	s_waitcnt lgkmcnt(0)
	v_add_u32_e32 v98, s65, v131
	ds_read_b64_tr_b16 v[96:97], v98 offset:8192
	ds_read_b64_tr_b16 v[98:99], v98 offset:10752
	v_add_u32_e32 v142, s65, v132
	v_exp_f32_e32 v56, v56
	v_exp_f32_e32 v57, v57
	v_exp_f32_e32 v58, v58
	v_exp_f32_e32 v59, v59
	v_exp_f32_e32 v60, v60
	v_exp_f32_e32 v61, v61
	v_exp_f32_e32 v62, v62
	v_exp_f32_e32 v63, v63
	v_exp_f32_e32 v72, v72
	v_exp_f32_e32 v73, v73
	v_exp_f32_e32 v74, v74
	v_exp_f32_e32 v75, v75
	v_exp_f32_e32 v76, v76
	v_exp_f32_e32 v77, v77
	v_exp_f32_e32 v78, v78
	v_exp_f32_e32 v79, v79
	ds_read_b64_tr_b16 v[156:157], v142 offset:8192
	ds_read_b64_tr_b16 v[158:159], v142 offset:10752
	v_exp_f32_e32 v64, v64
	v_exp_f32_e32 v65, v65
	v_exp_f32_e32 v66, v66
	v_exp_f32_e32 v67, v67
	v_exp_f32_e32 v68, v68
	v_exp_f32_e32 v69, v69
	v_exp_f32_e32 v70, v70
	v_exp_f32_e32 v71, v71
	v_cvt_pk_bf16_f32 v88, v56, v57
	v_cvt_pk_bf16_f32 v89, v58, v59
	v_cvt_pk_bf16_f32 v90, v60, v61
	v_cvt_pk_bf16_f32 v91, v62, v63
	v_exp_f32_e32 v80, v80
	v_exp_f32_e32 v81, v81
	v_exp_f32_e32 v82, v82
	v_exp_f32_e32 v83, v83
	v_exp_f32_e32 v84, v84
	v_exp_f32_e32 v85, v85
	v_exp_f32_e32 v86, v86
	v_exp_f32_e32 v87, v87
	v_cvt_pk_bf16_f32 v100, v72, v73
	v_cvt_pk_bf16_f32 v101, v74, v75
	v_cvt_pk_bf16_f32 v102, v76, v77
	v_cvt_pk_bf16_f32 v103, v78, v79
	v_add_u32_e32 v142, s65, v133
	s_waitcnt lgkmcnt(0)
	v_mfma_f32_16x16x32_bf16 v[28:31], v[96:99], v[88:91], v[28:31]
	ds_read_b64_tr_b16 v[164:165], v142 offset:8192
	v_cvt_pk_bf16_f32 v92, v64, v65
	v_cvt_pk_bf16_f32 v93, v66, v67
	v_mfma_f32_16x16x32_bf16 v[12:15], v[96:99], v[100:103], v[12:15]
	ds_read_b64_tr_b16 v[166:167], v142 offset:10752
	v_cvt_pk_bf16_f32 v94, v68, v69
	v_cvt_pk_bf16_f32 v95, v70, v71
	v_cvt_pk_bf16_f32 v160, v80, v81
	v_cvt_pk_bf16_f32 v161, v82, v83
	v_cvt_pk_bf16_f32 v162, v84, v85
	v_cvt_pk_bf16_f32 v163, v86, v87
	v_add_u32_e32 v98, s65, v134
	v_mfma_f32_16x16x32_bf16 v[28:31], v[156:159], v[92:95], v[28:31]
	ds_read_b64_tr_b16 v[96:97], v98 offset:8192
	v_add_u32_e32 v146, s65, v135
	v_add_f32_e64 v142, v56, 0
	v_add_f32_e64 v143, v57, 0
	v_mfma_f32_16x16x32_bf16 v[12:15], v[156:159], v[160:163], v[12:15]
	ds_read_b64_tr_b16 v[98:99], v98 offset:10752
	v_add_f32_e32 v142, v58, v142
	v_add_f32_e32 v143, v59, v143
	s_waitcnt lgkmcnt(0)
	v_mfma_f32_16x16x32_bf16 v[24:27], v[164:167], v[88:91], v[24:27]
	ds_read_b64_tr_b16 v[156:157], v146 offset:8192
	v_add_f32_e32 v142, v60, v142
	v_add_f32_e32 v143, v61, v143
	v_mfma_f32_16x16x32_bf16 v[8:11], v[164:167], v[100:103], v[8:11]
	ds_read_b64_tr_b16 v[158:159], v146 offset:10752
	v_add_u32_e32 v146, s65, v137
	v_add_f32_e32 v142, v62, v142
	v_add_f32_e32 v143, v63, v143
	v_mfma_f32_16x16x32_bf16 v[24:27], v[96:99], v[92:95], v[24:27]
	ds_read_b64_tr_b16 v[164:165], v146 offset:8192
	v_mfma_f32_16x16x32_bf16 v[8:11], v[96:99], v[160:163], v[8:11]
	ds_read_b64_tr_b16 v[166:167], v146 offset:10752
	v_add_f32_e32 v96, v64, v142
	v_add_f32_e32 v97, v65, v143
	v_add_u32_e32 v146, s65, v138
	v_add_f32_e32 v96, v66, v96
	v_add_f32_e32 v97, v67, v97
	s_waitcnt lgkmcnt(0)
	v_mfma_f32_16x16x32_bf16 v[20:23], v[156:159], v[88:91], v[20:23]
	v_add_f32_e64 v98, v68, v96
	v_add_f32_e64 v99, v69, v97
	ds_read_b64_tr_b16 v[96:97], v146 offset:8192
	v_add_f32_e32 v142, v70, v98
	v_add_f32_e32 v143, v71, v99
	v_mfma_f32_16x16x32_bf16 v[4:7], v[156:159], v[100:103], v[4:7]
	ds_read_b64_tr_b16 v[98:99], v146 offset:10752
	v_add_f32_e64 v156, v72, 0
	v_add_f32_e64 v157, v73, 0
	v_add_u32_e32 v146, s65, v139
	v_add_f32_e32 v158, v74, v156
	v_add_f32_e32 v159, v75, v157
	v_mfma_f32_16x16x32_bf16 v[20:23], v[164:167], v[92:95], v[20:23]
	v_add_f32_e64 v158, v76, v158
	v_add_f32_e64 v159, v77, v159
	ds_read_b64_tr_b16 v[156:157], v146 offset:8192
	v_mfma_f32_16x16x32_bf16 v[4:7], v[164:167], v[160:163], v[4:7]
	v_add_f32_e64 v164, v78, v158
	v_add_f32_e64 v165, v79, v159
	ds_read_b64_tr_b16 v[158:159], v146 offset:10752
	s_waitcnt lgkmcnt(0)
	v_mfma_f32_16x16x32_bf16 v[16:19], v[96:99], v[88:91], v[16:19]
	v_add_f32_e64 v88, v80, v164
	v_add_f32_e64 v89, v81, v165
	v_mov_b32_e32 v91, v142
	v_add_f32_e32 v88, v82, v88
	v_add_f32_e32 v89, v83, v89
	v_mfma_f32_16x16x32_bf16 v[0:3], v[96:99], v[100:103], v[0:3]
	v_add_f32_e64 v88, v84, v88
	v_add_f32_e64 v89, v85, v89
	v_add_f32_e32 v88, v86, v88
	v_add_f32_e32 v89, v87, v89
	v_mfma_f32_16x16x32_bf16 v[16:19], v[156:159], v[92:95], v[16:19]
	v_mov_b32_e32 v90, v88
	v_mov_b32_e32 v142, v89
	v_add_f32_e32 v88, v90, v142
	v_add_f32_e32 v89, v91, v143
	v_mfma_f32_16x16x32_bf16 v[0:3], v[156:159], v[160:163], v[0:3]
	v_add_f32_e64 v104, v104, v88
	v_add_f32_e64 v105, v105, v89

; #define ATT_BAR() asm volatile("s_waitcnt lgkmcnt(0)\n\ts_barrier" ::: "memory")
; template <int DQK, int MODE> __device__ __forceinline__ void attn_pass(LAS unsigned char* lds, const bf16* K0, int p0, const bf16* K1, int p1, const bf16* V, int pv, int tlo, int thi, ...
;     ...
;     if (grp == 0) ATT_BAR(); else __builtin_amdgcn_s_setprio(0);
.LBB0_1220:
	s_andn2_b64 vcc, exec, s[6:7]
	s_cbranch_vccnz .LBB0_982
	s_waitcnt lgkmcnt(0)
	s_branch .LBB0_982
